# P2: sample-stream wave batches K and V loads (3 round trips per tile instead of 25); conversion loop keeps next item loads in flight (counted vmcnt)
# speedup vs baseline: 1.0043x; 1.0043x over previous
; #define LAS __attribute__((address_space(3)))
; __device__ __forceinline__ void tr_load(const ItemD& d, int lane, f32x4 (&v)[16]) {
;     const float* src = d.W + (size_t)(lane >> 4) * d.ldw + (lane & 15) * 4;
; #pragma unroll
;     for (int i = 0; i < 16; ++i) v[i] = *(const f32x4*)(src + (size_t)(4 * i) * d.ldw);
; }
; __device__ __forceinline__ void convert_items(LAS float* scr, int lane, int it_lo, int it_hi, int cw, int ncw) {
;     asm volatile("" : "+v"(lane));
;     int it = it_lo + cw; if (it >= it_hi) return;
;     ItemD d0 = decode_item(it), d1 = d0; f32x4 v0[16], v1[16];
;     tr_load(d0, lane, v0);
;     for (;;) {
;         it += ncw; const bool h1 = it < it_hi;
;         if (h1) { d1 = decode_item(it); tr_load(d1, lane, v1); }
;         tr_store(d0, lane, v0, scr);
;         if (!h1) break;
;         it += ncw; const bool h0 = it < it_hi;
;         if (h0) { d0 = decode_item(it); tr_load(d0, lane, v0); }
;         tr_store(d1, lane, v1, scr);
;         if (!h0) break;
;     }
; }
.LBB0_462:
	s_and_b32 s10, 0xffff, s22
	s_cmp_lg_u32 s10, 0
	s_cselect_b64 s[10:11], -1, 0
	s_cmp_lg_u64 s[10:11], 0
	s_addc_u32 s62, s44, 0
	s_lshl_b64 s[10:11], s[12:13], 1
	s_add_u32 s12, s14, s10
	s_addc_u32 s14, s15, s11
	s_lshl_b64 s[10:11], s[76:77], 1
	v_ashrrev_i32_e32 v128, 4, v64
	s_add_u32 s10, s12, s10
	v_ashrrev_i32_e32 v129, 31, v128
	s_addc_u32 s11, s14, s11
	v_mul_lo_u32 v2, s74, v129
	v_mul_lo_u32 v3, s75, v128
	v_mad_u64_u32 v[0:1], s[14:15], s74, v128, 0
	v_add3_u32 v1, v1, v2, v3
	v_lshlrev_b32_e32 v2, 2, v64
	v_and_b32_e32 v130, 60, v2
	v_lshl_add_u64 v[0:1], v[0:1], 2, s[72:73]
	v_lshlrev_b32_e32 v160, 2, v130
	v_lshl_add_u64 v[0:1], v[0:1], 0, v[160:161]
	s_lshl_b64 s[14:15], s[74:75], 4
	v_lshl_add_u64 v[8:9], v[0:1], 0, s[14:15]
	global_load_dwordx4 v[0:3], v[0:1], off
	s_nop 0
	global_load_dwordx4 v[4:7], v[8:9], off
	v_lshl_add_u64 v[8:9], v[8:9], 0, s[14:15]
	v_lshl_add_u64 v[16:17], v[8:9], 0, s[14:15]
	global_load_dwordx4 v[8:11], v[8:9], off
	s_nop 0
	global_load_dwordx4 v[12:15], v[16:17], off
	v_lshl_add_u64 v[16:17], v[16:17], 0, s[14:15]
	v_lshl_add_u64 v[24:25], v[16:17], 0, s[14:15]
	global_load_dwordx4 v[16:19], v[16:17], off
	s_nop 0
	global_load_dwordx4 v[20:23], v[24:25], off
	v_lshl_add_u64 v[24:25], v[24:25], 0, s[14:15]
	v_lshl_add_u64 v[32:33], v[24:25], 0, s[14:15]
	v_lshl_add_u64 v[36:37], v[32:33], 0, s[14:15]
	v_lshl_add_u64 v[40:41], v[36:37], 0, s[14:15]
	v_lshl_add_u64 v[44:45], v[40:41], 0, s[14:15]
	v_lshl_add_u64 v[48:49], v[44:45], 0, s[14:15]
	v_lshl_add_u64 v[52:53], v[48:49], 0, s[14:15]
	v_lshl_add_u64 v[56:57], v[52:53], 0, s[14:15]
	v_lshl_add_u64 v[60:61], v[56:57], 0, s[14:15]
	global_load_dwordx4 v[24:27], v[24:25], off
	s_nop 0
	global_load_dwordx4 v[28:31], v[32:33], off
	v_ashrrev_i32_e32 v132, 3, v64
	global_load_dwordx4 v[32:35], v[36:37], off
	v_lshlrev_b32_e32 v64, 3, v64
	global_load_dwordx4 v[36:39], v[40:41], off
	v_and_b32_e32 v134, 56, v64
	global_load_dwordx4 v[40:43], v[44:45], off
	s_mul_i32 s12, s62, 3
	global_load_dwordx4 v[44:47], v[48:49], off
	v_mul_u32_u24_e32 v64, 0x104, v134
	global_load_dwordx4 v[48:51], v[52:53], off
	v_lshlrev_b32_e32 v67, 2, v132
	global_load_dwordx4 v[52:55], v[56:57], off
	v_add_u32_e32 v136, 8, v132
	global_load_dwordx4 v[56:59], v[60:61], off
	v_lshl_add_u64 v[60:61], v[60:61], 0, s[14:15]
	global_load_dwordx4 v[60:63], v[60:61], off
	s_movk_i32 s14, 0x104
	v_readlane_b32 s15, v250, 15
	v_mul_lo_u32 v66, v128, s14
	v_readlane_b32 s14, v250, 0
	v_add_u32_e32 v65, s15, v160
	v_add3_u32 v172, s15, v64, v67
	v_add_u32_e32 v138, 16, v132
	v_add_u32_e32 v140, 24, v132
	v_add_u32_e32 v142, 32, v132
	v_add_u32_e32 v162, 40, v132
	v_add_u32_e32 v164, 48, v132
	v_add_u32_e32 v166, 56, v132
	s_mul_i32 s33, s62, 6
	s_mul_i32 s89, s62, 48
	v_readlane_b32 s15, v250, 21
	s_add_i32 s23, s14, s12
	s_mul_i32 s12, s62, 24
	v_ashrrev_i32_e32 v131, 31, v132
	v_ashrrev_i32_e32 v133, 31, v136
	v_ashrrev_i32_e32 v135, 31, v138
	v_ashrrev_i32_e32 v137, 31, v140
	v_ashrrev_i32_e32 v139, 31, v142
	v_ashrrev_i32_e32 v141, 31, v162
	v_ashrrev_i32_e32 v143, 31, v164
	v_ashrrev_i32_e32 v163, 31, v166
	s_add_i32 s88, s14, s33
	s_add_i32 s39, s15, s89
	s_mul_i32 s22, s62, 0x180
	s_add_i32 s35, s15, s12
	s_mulk_i32 s62, 0xc0
	v_add_u32_e32 v173, v65, v66
	v_readlane_b32 s63, v250, 25
	v_readlane_b32 s94, v250, 23
	s_mov_b32 s97, s5
	s_mov_b64 s[14:15], s[10:11]
	s_branch .LBB0_466
.LBB0_463:
	s_waitcnt lgkmcnt(0)
	s_lshl_b64 s[10:11], s[12:13], 1
	s_add_u32 s12, s72, s10
	s_addc_u32 s72, s73, s11
	s_lshl_b64 s[10:11], s[76:77], 1
	s_add_u32 s10, s12, s10
	s_addc_u32 s11, s72, s11
	v_mul_lo_u32 v2, s79, v128
	v_mul_lo_u32 v3, s78, v129
	v_mad_u64_u32 v[0:1], s[72:73], s78, v128, 0
	v_add3_u32 v1, v1, v3, v2
	v_lshl_add_u64 v[0:1], v[0:1], 2, s[74:75]
	v_lshlrev_b32_e32 v2, 2, v130
	v_mov_b32_e32 v3, v161
	v_lshl_add_u64 v[0:1], v[0:1], 0, v[2:3]
	s_lshl_b64 s[72:73], s[78:79], 4
	v_lshl_add_u64 v[8:9], v[0:1], 0, s[72:73]
	global_load_dwordx4 v[0:3], v[0:1], off
	s_nop 0
	global_load_dwordx4 v[4:7], v[8:9], off
	v_lshl_add_u64 v[8:9], v[8:9], 0, s[72:73]
	v_lshl_add_u64 v[16:17], v[8:9], 0, s[72:73]
	global_load_dwordx4 v[8:11], v[8:9], off
	s_nop 0
	global_load_dwordx4 v[12:15], v[16:17], off
	v_lshl_add_u64 v[16:17], v[16:17], 0, s[72:73]
	v_lshl_add_u64 v[24:25], v[16:17], 0, s[72:73]
	global_load_dwordx4 v[16:19], v[16:17], off
	s_nop 0
	global_load_dwordx4 v[20:23], v[24:25], off
	v_lshl_add_u64 v[24:25], v[24:25], 0, s[72:73]
	v_lshl_add_u64 v[32:33], v[24:25], 0, s[72:73]
	v_lshl_add_u64 v[36:37], v[32:33], 0, s[72:73]
	v_lshl_add_u64 v[40:41], v[36:37], 0, s[72:73]
	v_lshl_add_u64 v[44:45], v[40:41], 0, s[72:73]
	v_lshl_add_u64 v[48:49], v[44:45], 0, s[72:73]
	v_lshl_add_u64 v[52:53], v[48:49], 0, s[72:73]
	v_lshl_add_u64 v[56:57], v[52:53], 0, s[72:73]
	v_lshl_add_u64 v[60:61], v[56:57], 0, s[72:73]
	global_load_dwordx4 v[24:27], v[24:25], off
	s_nop 0
	global_load_dwordx4 v[28:31], v[32:33], off
	s_nop 0
	global_load_dwordx4 v[32:35], v[36:37], off
	s_nop 0
	global_load_dwordx4 v[36:39], v[40:41], off
	s_nop 0
	global_load_dwordx4 v[40:43], v[44:45], off
	s_nop 0
	global_load_dwordx4 v[44:47], v[48:49], off
	s_nop 0
	global_load_dwordx4 v[48:51], v[52:53], off
	s_nop 0
	global_load_dwordx4 v[52:55], v[56:57], off
	s_nop 0
	global_load_dwordx4 v[56:59], v[60:61], off
	v_lshl_add_u64 v[60:61], v[60:61], 0, s[72:73]
	global_load_dwordx4 v[60:63], v[60:61], off
	s_waitcnt vmcnt(16)
	s_branch .LBB0_464

; #define LAS __attribute__((address_space(3)))
; __device__ __forceinline__ unsigned pk2(float lo, float hi) { const bf16x2_t v = __builtin_convertvector((f32x2_t){lo, hi}, bf16x2_t); return __builtin_bit_cast(unsigned, v); }
; #define LDS_WAIT() asm volatile("s_waitcnt lgkmcnt(0)" ::: "memory")
; __device__ __forceinline__ void tr_store(const ItemD& d, int lane, const f32x4 (&v)[16], LAS float* scr) {
; #pragma unroll
;     for (int i = 0; i < 16; ++i) { LAS float* q = scr + (4 * i + (lane >> 4)) * 65 + (lane & 15) * 4; q[0] = v[i].x; q[1] = v[i].y; q[2] = v[i].z; q[3] = v[i].w; }
;     LDS_WAIT();
;     const int c = lane & 7;
; #pragma unroll
;     for (int j = 0; j < 8; ++j) {
;         const int n = (lane >> 3) + 8 * j; const LAS float* s = scr + (8 * c) * 65 + n;
;         u32x4 o; o.x = pk2(s[0], s[65]); o.y = pk2(s[130], s[195]); o.z = pk2(s[260], s[325]); o.w = pk2(s[390], s[455]);
;         *(u32x4*)(d.WT + (size_t)n * d.ldt + 8 * c) = o;
;     }
.LBB0_464:
	ds_write2_b32 v173, v68, v69 offset1:1
	ds_write2_b32 v173, v70, v71 offset0:2 offset1:3
	ds_write2_b32 v174, v64, v65 offset1:1
	ds_write2_b32 v175, v66, v67 offset1:1
	ds_write2_b32 v176, v76, v77 offset1:1
	ds_write2_b32 v177, v78, v79 offset1:1
	ds_write2_b32 v178, v72, v73 offset1:1
	ds_write2_b32 v179, v74, v75 offset1:1
	ds_write2_b32 v180, v84, v85 offset1:1
	ds_write2_b32 v181, v86, v87 offset1:1
	ds_write2_b32 v182, v80, v81 offset1:1
	ds_write2_b32 v183, v82, v83 offset1:1
	ds_write2_b32 v184, v92, v93 offset1:1
	ds_write2_b32 v185, v94, v95 offset1:1
	ds_write2_b32 v186, v88, v89 offset1:1
	ds_write2_b32 v187, v90, v91 offset1:1
	ds_write2_b32 v188, v96, v97 offset1:1
	ds_write2_b32 v189, v98, v99 offset1:1
	ds_write2_b32 v190, v100, v101 offset1:1
	ds_write2_b32 v191, v102, v103 offset1:1
	ds_write2_b32 v218, v104, v105 offset1:1
	ds_write2_b32 v219, v106, v107 offset1:1
	ds_write2_b32 v220, v108, v109 offset1:1
	ds_write2_b32 v221, v110, v111 offset1:1
	ds_write2_b32 v222, v112, v113 offset1:1
	ds_write2_b32 v223, v114, v115 offset1:1
	ds_write2_b32 v224, v116, v117 offset1:1
	ds_write2_b32 v225, v118, v119 offset1:1
	ds_write2_b32 v226, v120, v121 offset1:1
	ds_write2_b32 v227, v122, v123 offset1:1
	ds_write2_b32 v228, v124, v125 offset1:1
	ds_write2_b32 v229, v126, v127 offset1:1
	s_waitcnt lgkmcnt(0)
	ds_read_b32 v174, v172
	ds_read_b32 v175, v172 offset:260
	ds_read_b32 v176, v172 offset:520
	ds_read_b32 v177, v172 offset:780
	ds_read_b32 v178, v172 offset:1040
	ds_read_b32 v179, v172 offset:1300
	ds_read_b32 v180, v172 offset:1560
	ds_read_b32 v181, v172 offset:1820
	s_waitcnt lgkmcnt(0)
	v_cvt_pk_bf16_f32 v174, v174, v175
	v_cvt_pk_bf16_f32 v175, v176, v177
	v_cvt_pk_bf16_f32 v176, v178, v179
	v_mad_u64_u32 v[178:179], s[72:73], s97, v132, 0
	v_lshl_add_u64 v[168:169], s[14:15], 0, v[160:161]
	v_mov_b32_e32 v160, v179
	v_cvt_pk_bf16_f32 v177, v180, v181
	v_mad_u64_u32 v[180:181], s[72:73], s97, v131, v[160:161]
	v_mov_b32_e32 v179, v180
	v_lshl_add_u64 v[178:179], v[178:179], 1, v[168:169]
	global_store_dwordx4 v[178:179], v[174:177], off
	ds_read_b32 v160, v172 offset:32
	ds_read_b32 v174, v172 offset:292
	ds_read_b32 v175, v172 offset:552
	ds_read_b32 v176, v172 offset:812
	ds_read_b32 v177, v172 offset:1072
	ds_read_b32 v178, v172 offset:1332
	ds_read_b32 v179, v172 offset:1592
	ds_read_b32 v180, v172 offset:1852
	s_waitcnt lgkmcnt(0)
	v_cvt_pk_bf16_f32 v175, v175, v176
	v_cvt_pk_bf16_f32 v174, v160, v174
	v_cvt_pk_bf16_f32 v176, v177, v178
	s_add_i32 s63, s63, s33
	v_cvt_pk_bf16_f32 v177, v179, v180
	v_mad_u64_u32 v[178:179], s[72:73], s97, v136, 0
	v_mov_b32_e32 v160, v179
	v_mad_u64_u32 v[180:181], s[72:73], s97, v133, v[160:161]
	v_mov_b32_e32 v179, v180
	v_lshl_add_u64 v[178:179], v[178:179], 1, v[168:169]
	global_store_dwordx4 v[178:179], v[174:177], off
	ds_read_b32 v160, v172 offset:64
	ds_read_b32 v174, v172 offset:324
	ds_read_b32 v175, v172 offset:584
	ds_read_b32 v176, v172 offset:844
	ds_read_b32 v177, v172 offset:1104
	ds_read_b32 v178, v172 offset:1364
	ds_read_b32 v179, v172 offset:1624
	ds_read_b32 v180, v172 offset:1884
	s_waitcnt lgkmcnt(0)
	v_cvt_pk_bf16_f32 v175, v175, v176
	v_cvt_pk_bf16_f32 v174, v160, v174
	v_cvt_pk_bf16_f32 v176, v177, v178
	s_add_i32 s88, s88, s33
	v_cvt_pk_bf16_f32 v177, v179, v180
	v_mad_u64_u32 v[178:179], s[72:73], s97, v138, 0
	v_mov_b32_e32 v160, v179
	v_mad_u64_u32 v[180:181], s[72:73], s97, v135, v[160:161]
	v_mov_b32_e32 v179, v180
	v_lshl_add_u64 v[178:179], v[178:179], 1, v[168:169]
	global_store_dwordx4 v[178:179], v[174:177], off
	ds_read_b32 v160, v172 offset:96
	ds_read_b32 v174, v172 offset:356
	ds_read_b32 v175, v172 offset:616
	ds_read_b32 v176, v172 offset:876
	ds_read_b32 v177, v172 offset:1136
	ds_read_b32 v178, v172 offset:1396
	ds_read_b32 v179, v172 offset:1656
	ds_read_b32 v180, v172 offset:1916
	s_waitcnt lgkmcnt(0)
; #define LAS __attribute__((address_space(3)))
; __device__ __forceinline__ unsigned pk2(float lo, float hi) { const bf16x2_t v = __builtin_convertvector((f32x2_t){lo, hi}, bf16x2_t); return __builtin_bit_cast(unsigned, v); }
; __device__ __forceinline__ void tr_store(const ItemD& d, int lane, const f32x4 (&v)[16], LAS float* scr) {
;     ...
;     for (int j = 0; j < 8; ++j) {
;         const int n = (lane >> 3) + 8 * j; const LAS float* s = scr + (8 * c) * 65 + n;
;         u32x4 o; o.x = pk2(s[0], s[65]); o.y = pk2(s[130], s[195]); o.z = pk2(s[260], s[325]); o.w = pk2(s[390], s[455]);
;         *(u32x4*)(d.WT + (size_t)n * d.ldt + 8 * c) = o;
;     }
	v_cvt_pk_bf16_f32 v175, v175, v176
	v_cvt_pk_bf16_f32 v174, v160, v174
	v_cvt_pk_bf16_f32 v176, v177, v178
	s_add_i32 s39, s39, s89
	v_cvt_pk_bf16_f32 v177, v179, v180
	v_mad_u64_u32 v[178:179], s[72:73], s97, v140, 0
	v_mov_b32_e32 v160, v179
	v_mad_u64_u32 v[180:181], s[72:73], s97, v137, v[160:161]
	v_mov_b32_e32 v179, v180
	v_lshl_add_u64 v[178:179], v[178:179], 1, v[168:169]
	global_store_dwordx4 v[178:179], v[174:177], off
	ds_read_b32 v160, v172 offset:128
	ds_read_b32 v174, v172 offset:388
	ds_read_b32 v175, v172 offset:648
	ds_read_b32 v176, v172 offset:908
	ds_read_b32 v177, v172 offset:1168
	ds_read_b32 v178, v172 offset:1428
	ds_read_b32 v179, v172 offset:1688
	ds_read_b32 v180, v172 offset:1948
	s_waitcnt lgkmcnt(0)
	v_cvt_pk_bf16_f32 v175, v175, v176
	v_cvt_pk_bf16_f32 v174, v160, v174
	v_cvt_pk_bf16_f32 v176, v177, v178
	s_add_i32 s94, s94, s22
	v_cvt_pk_bf16_f32 v177, v179, v180
	v_mad_u64_u32 v[178:179], s[72:73], s97, v142, 0
	v_mov_b32_e32 v160, v179
	v_mad_u64_u32 v[180:181], s[72:73], s97, v139, v[160:161]
	v_mov_b32_e32 v179, v180
	v_lshl_add_u64 v[178:179], v[178:179], 1, v[168:169]
	global_store_dwordx4 v[178:179], v[174:177], off
	ds_read_b32 v160, v172 offset:160
	ds_read_b32 v174, v172 offset:420
	ds_read_b32 v175, v172 offset:680
	ds_read_b32 v176, v172 offset:940
	ds_read_b32 v177, v172 offset:1200
	ds_read_b32 v178, v172 offset:1460
	ds_read_b32 v179, v172 offset:1720
	ds_read_b32 v180, v172 offset:1980
	s_waitcnt lgkmcnt(0)
	v_cvt_pk_bf16_f32 v175, v175, v176
	v_cvt_pk_bf16_f32 v174, v160, v174
	v_cvt_pk_bf16_f32 v176, v177, v178
	s_add_i32 s23, s23, s33
	v_cvt_pk_bf16_f32 v177, v179, v180
	v_mad_u64_u32 v[178:179], s[72:73], s97, v162, 0
	v_mov_b32_e32 v160, v179
	v_mad_u64_u32 v[180:181], s[72:73], s97, v141, v[160:161]
	v_mov_b32_e32 v179, v180
	v_lshl_add_u64 v[178:179], v[178:179], 1, v[168:169]
	global_store_dwordx4 v[178:179], v[174:177], off
	ds_read_b32 v160, v172 offset:192
	ds_read_b32 v174, v172 offset:452
	ds_read_b32 v175, v172 offset:712
	ds_read_b32 v176, v172 offset:972
	ds_read_b32 v177, v172 offset:1232
	ds_read_b32 v178, v172 offset:1492
	ds_read_b32 v179, v172 offset:1752
	ds_read_b32 v180, v172 offset:2012
	s_waitcnt lgkmcnt(0)
	v_cvt_pk_bf16_f32 v175, v175, v176
	v_cvt_pk_bf16_f32 v174, v160, v174
	v_cvt_pk_bf16_f32 v176, v177, v178
	s_add_i32 s35, s35, s89
	v_cvt_pk_bf16_f32 v177, v179, v180
	v_mad_u64_u32 v[178:179], s[72:73], s97, v164, 0
	v_mov_b32_e32 v160, v179
	v_mad_u64_u32 v[180:181], s[72:73], s97, v143, v[160:161]
	v_mov_b32_e32 v179, v180
	v_lshl_add_u64 v[178:179], v[178:179], 1, v[168:169]
	global_store_dwordx4 v[178:179], v[174:177], off
	ds_read_b32 v160, v172 offset:224
	ds_read_b32 v174, v172 offset:484
	ds_read_b32 v175, v172 offset:744
	ds_read_b32 v176, v172 offset:1004
	ds_read_b32 v177, v172 offset:1264
	ds_read_b32 v178, v172 offset:1524
	ds_read_b32 v179, v172 offset:1784
	ds_read_b32 v180, v172 offset:2044
	s_waitcnt lgkmcnt(0)
	v_cvt_pk_bf16_f32 v175, v175, v176
	v_cvt_pk_bf16_f32 v174, v160, v174
	v_cvt_pk_bf16_f32 v176, v177, v178
	s_add_i32 s12, s84, s63
	v_cvt_pk_bf16_f32 v177, v179, v180
	v_mad_u64_u32 v[178:179], s[72:73], s97, v166, 0
	v_mov_b32_e32 v160, v179
	v_mad_u64_u32 v[180:181], s[72:73], s97, v163, v[160:161]
	v_mov_b32_e32 v179, v180
	v_lshl_add_u64 v[168:169], v[178:179], 1, v[168:169]
	global_store_dwordx4 v[168:169], v[174:177], off
	s_waitcnt lgkmcnt(0)
	s_cmp_gt_i32 s12, 0xb1ff
	s_cselect_b64 s[74:75], -1, 0

; __device__ __forceinline__ void tr_load(const ItemD& d, int lane, f32x4 (&v)[16]) {
;     const float* src = d.W + (size_t)(lane >> 4) * d.ldw + (lane & 15) * 4;
; #pragma unroll
;     for (int i = 0; i < 16; ++i) v[i] = *(const f32x4*)(src + (size_t)(4 * i) * d.ldw);
; }
; __device__ __forceinline__ void convert_items(LAS float* scr, int lane, int it_lo, int it_hi, int cw, int ncw) {
;     ...
;         it += ncw; const bool h1 = it < it_hi;
;         if (h1) { d1 = decode_item(it); tr_load(d1, lane, v1); }
;         tr_store(d0, lane, v0, scr);
;         if (!h1) break;
;         it += ncw; const bool h0 = it < it_hi;
;         if (h0) { d0 = decode_item(it); tr_load(d0, lane, v0); }
.LBB0_482:
	s_waitcnt lgkmcnt(0)
	s_lshl_b64 s[14:15], s[12:13], 1
	s_add_u32 s12, s74, s14
	s_addc_u32 s74, s75, s15
	s_lshl_b64 s[14:15], s[78:79], 1
	s_add_u32 s14, s12, s14
	s_addc_u32 s15, s74, s15
	v_mul_lo_u32 v66, s81, v128
	v_mul_lo_u32 v67, s80, v129
	v_mad_u64_u32 v[64:65], s[74:75], s80, v128, 0
	v_add3_u32 v65, v65, v67, v66
	v_lshl_add_u64 v[64:65], v[64:65], 2, s[76:77]
	v_lshlrev_b32_e32 v160, 2, v130
	v_lshl_add_u64 v[64:65], v[64:65], 0, v[160:161]
	s_lshl_b64 s[74:75], s[80:81], 4
	v_lshl_add_u64 v[72:73], v[64:65], 0, s[74:75]
	global_load_dwordx4 v[68:71], v[64:65], off
	s_nop 0
	global_load_dwordx4 v[64:67], v[72:73], off
	v_lshl_add_u64 v[72:73], v[72:73], 0, s[74:75]
	v_lshl_add_u64 v[80:81], v[72:73], 0, s[74:75]
	global_load_dwordx4 v[76:79], v[72:73], off
	s_nop 0
	global_load_dwordx4 v[72:75], v[80:81], off
	v_lshl_add_u64 v[80:81], v[80:81], 0, s[74:75]
	v_lshl_add_u64 v[88:89], v[80:81], 0, s[74:75]
	global_load_dwordx4 v[84:87], v[80:81], off
	s_nop 0
	global_load_dwordx4 v[80:83], v[88:89], off
	v_lshl_add_u64 v[88:89], v[88:89], 0, s[74:75]
	v_lshl_add_u64 v[96:97], v[88:89], 0, s[74:75]
	v_lshl_add_u64 v[100:101], v[96:97], 0, s[74:75]
	v_lshl_add_u64 v[104:105], v[100:101], 0, s[74:75]
	v_lshl_add_u64 v[108:109], v[104:105], 0, s[74:75]
	v_lshl_add_u64 v[112:113], v[108:109], 0, s[74:75]
	v_lshl_add_u64 v[116:117], v[112:113], 0, s[74:75]
	v_lshl_add_u64 v[120:121], v[116:117], 0, s[74:75]
	v_lshl_add_u64 v[124:125], v[120:121], 0, s[74:75]
	global_load_dwordx4 v[92:95], v[88:89], off
	s_nop 0
	global_load_dwordx4 v[88:91], v[96:97], off
	s_nop 0
	global_load_dwordx4 v[96:99], v[100:101], off
	s_nop 0
	global_load_dwordx4 v[100:103], v[104:105], off
	s_nop 0
	global_load_dwordx4 v[104:107], v[108:109], off
	s_nop 0
	global_load_dwordx4 v[108:111], v[112:113], off
	s_nop 0
	global_load_dwordx4 v[112:115], v[116:117], off
	s_nop 0
	global_load_dwordx4 v[116:119], v[120:121], off
	s_nop 0
	global_load_dwordx4 v[120:123], v[124:125], off
	v_lshl_add_u64 v[124:125], v[124:125], 0, s[74:75]
	global_load_dwordx4 v[124:127], v[124:125], off
	s_waitcnt vmcnt(16)
	s_branch .LBB0_483

; #define LAS __attribute__((address_space(3)))
; __device__ __forceinline__ unsigned pk2(float lo, float hi) { const bf16x2_t v = __builtin_convertvector((f32x2_t){lo, hi}, bf16x2_t); return __builtin_bit_cast(unsigned, v); }
; #define LDS_WAIT() asm volatile("s_waitcnt lgkmcnt(0)" ::: "memory")
; __device__ __forceinline__ void tr_store(const ItemD& d, int lane, const f32x4 (&v)[16], LAS float* scr) {
; #pragma unroll
;     for (int i = 0; i < 16; ++i) { LAS float* q = scr + (4 * i + (lane >> 4)) * 65 + (lane & 15) * 4; q[0] = v[i].x; q[1] = v[i].y; q[2] = v[i].z; q[3] = v[i].w; }
;     LDS_WAIT();
;     const int c = lane & 7;
; #pragma unroll
;     for (int j = 0; j < 8; ++j) {
;         const int n = (lane >> 3) + 8 * j; const LAS float* s = scr + (8 * c) * 65 + n;
;         u32x4 o; o.x = pk2(s[0], s[65]); o.y = pk2(s[130], s[195]); o.z = pk2(s[260], s[325]); o.w = pk2(s[390], s[455]);
;         *(u32x4*)(d.WT + (size_t)n * d.ldt + 8 * c) = o;
;     }
.LBB0_483:
	v_add_u32_e32 v174, 0x410, v173
	v_add_u32_e32 v175, 0x418, v173
	v_add_u32_e32 v176, 0x820, v173
	v_add_u32_e32 v177, 0x828, v173
	v_add_u32_e32 v178, 0xc30, v173
	v_add_u32_e32 v179, 0xc38, v173
	v_add_u32_e32 v180, 0x1040, v173
	v_add_u32_e32 v181, 0x1048, v173
	v_add_u32_e32 v182, 0x1450, v173
	v_add_u32_e32 v183, 0x1458, v173
	v_add_u32_e32 v184, 0x1860, v173
	v_add_u32_e32 v185, 0x1868, v173
	v_add_u32_e32 v186, 0x1c70, v173
	v_add_u32_e32 v187, 0x1c78, v173
	v_add_u32_e32 v188, 0x2080, v173
	v_add_u32_e32 v189, 0x2088, v173
	v_add_u32_e32 v190, 0x2490, v173
	v_add_u32_e32 v191, 0x2498, v173
	v_add_u32_e32 v218, 0x28a0, v173
	v_add_u32_e32 v219, 0x28a8, v173
	v_add_u32_e32 v220, 0x2cb0, v173
	v_add_u32_e32 v221, 0x2cb8, v173
	v_add_u32_e32 v222, 0x30c0, v173
	v_add_u32_e32 v223, 0x30c8, v173
	v_add_u32_e32 v224, 0x34d0, v173
	v_add_u32_e32 v225, 0x34d8, v173
	v_add_u32_e32 v226, 0x38e0, v173
	v_add_u32_e32 v227, 0x38e8, v173
	v_add_u32_e32 v228, 0x3cf0, v173
	v_add_u32_e32 v229, 0x3cf8, v173
	s_waitcnt lgkmcnt(0)
	ds_write2_b32 v173, v0, v1 offset1:1
	ds_write2_b32 v173, v2, v3 offset0:2 offset1:3
	ds_write2_b32 v174, v4, v5 offset1:1
	ds_write2_b32 v175, v6, v7 offset1:1
	ds_write2_b32 v176, v8, v9 offset1:1
	ds_write2_b32 v177, v10, v11 offset1:1
	ds_write2_b32 v178, v12, v13 offset1:1
	ds_write2_b32 v179, v14, v15 offset1:1
	ds_write2_b32 v180, v16, v17 offset1:1
	ds_write2_b32 v181, v18, v19 offset1:1
	ds_write2_b32 v182, v20, v21 offset1:1
	ds_write2_b32 v183, v22, v23 offset1:1
	ds_write2_b32 v184, v24, v25 offset1:1
	ds_write2_b32 v185, v26, v27 offset1:1
	ds_write2_b32 v186, v28, v29 offset1:1
	ds_write2_b32 v187, v30, v31 offset1:1
	ds_write2_b32 v188, v32, v33 offset1:1
	ds_write2_b32 v189, v34, v35 offset1:1
	ds_write2_b32 v190, v36, v37 offset1:1
	ds_write2_b32 v191, v38, v39 offset1:1
	ds_write2_b32 v218, v40, v41 offset1:1
	ds_write2_b32 v219, v42, v43 offset1:1
	ds_write2_b32 v220, v44, v45 offset1:1
	ds_write2_b32 v221, v46, v47 offset1:1
	ds_write2_b32 v222, v48, v49 offset1:1
	ds_write2_b32 v223, v50, v51 offset1:1
	ds_write2_b32 v224, v52, v53 offset1:1
	ds_write2_b32 v225, v54, v55 offset1:1
	ds_write2_b32 v226, v56, v57 offset1:1
	ds_write2_b32 v227, v58, v59 offset1:1
	ds_write2_b32 v228, v60, v61 offset1:1
	ds_write2_b32 v229, v62, v63 offset1:1
	s_waitcnt lgkmcnt(0)
	ds_read_b32 v230, v172
	ds_read_b32 v231, v172 offset:260
	v_lshlrev_b32_e32 v160, 1, v134
	v_lshl_add_u64 v[168:169], s[10:11], 0, v[160:161]
	s_andn2_b64 vcc, exec, s[72:73]
	s_waitcnt lgkmcnt(0)
	v_cvt_pk_bf16_f32 v230, v230, v231
	ds_read_b32 v231, v172 offset:520
	ds_read_b32 v232, v172 offset:780
	s_waitcnt lgkmcnt(0)
	v_cvt_pk_bf16_f32 v231, v231, v232
	ds_read_b32 v232, v172 offset:1040
	ds_read_b32 v233, v172 offset:1300
	s_waitcnt lgkmcnt(0)
	v_cvt_pk_bf16_f32 v232, v232, v233
	ds_read_b32 v233, v172 offset:1560
	ds_read_b32 v234, v172 offset:1820
	s_waitcnt lgkmcnt(0)
	v_cvt_pk_bf16_f32 v233, v233, v234
	v_mad_u64_u32 v[234:235], s[74:75], s5, v132, 0
	v_mov_b32_e32 v236, v235
	v_mad_u64_u32 v[236:237], s[74:75], s5, v131, v[236:237]
	v_mov_b32_e32 v235, v236
	v_lshl_add_u64 v[234:235], v[234:235], 1, v[168:169]
	global_store_dwordx4 v[234:235], v[230:233], off
	ds_read_b32 v230, v172 offset:32
	ds_read_b32 v231, v172 offset:292
	s_waitcnt lgkmcnt(0)
	v_cvt_pk_bf16_f32 v230, v230, v231
	ds_read_b32 v231, v172 offset:552
	ds_read_b32 v232, v172 offset:812
	s_waitcnt lgkmcnt(0)
	v_cvt_pk_bf16_f32 v231, v231, v232
	ds_read_b32 v232, v172 offset:1072
	ds_read_b32 v233, v172 offset:1332
	s_waitcnt lgkmcnt(0)
	v_cvt_pk_bf16_f32 v232, v232, v233
	ds_read_b32 v233, v172 offset:1592
	ds_read_b32 v234, v172 offset:1852
	s_waitcnt lgkmcnt(0)
	v_cvt_pk_bf16_f32 v233, v233, v234
	v_mad_u64_u32 v[234:235], s[74:75], s5, v136, 0
	v_mov_b32_e32 v236, v235
	v_mad_u64_u32 v[236:237], s[74:75], s5, v133, v[236:237]
	v_mov_b32_e32 v235, v236
	v_lshl_add_u64 v[234:235], v[234:235], 1, v[168:169]
	global_store_dwordx4 v[234:235], v[230:233], off
	ds_read_b32 v230, v172 offset:64
	ds_read_b32 v231, v172 offset:324
	s_waitcnt lgkmcnt(0)
	v_cvt_pk_bf16_f32 v230, v230, v231
	ds_read_b32 v231, v172 offset:584
	ds_read_b32 v232, v172 offset:844
	s_waitcnt lgkmcnt(0)
	v_cvt_pk_bf16_f32 v231, v231, v232
	ds_read_b32 v232, v172 offset:1104
	ds_read_b32 v233, v172 offset:1364
	s_waitcnt lgkmcnt(0)
	v_cvt_pk_bf16_f32 v232, v232, v233
	ds_read_b32 v233, v172 offset:1624
	ds_read_b32 v234, v172 offset:1884
	s_waitcnt lgkmcnt(0)
	v_cvt_pk_bf16_f32 v233, v233, v234
	v_mad_u64_u32 v[234:235], s[74:75], s5, v138, 0
	v_mov_b32_e32 v236, v235
	v_mad_u64_u32 v[236:237], s[74:75], s5, v135, v[236:237]
	v_mov_b32_e32 v235, v236
	v_lshl_add_u64 v[234:235], v[234:235], 1, v[168:169]
	global_store_dwordx4 v[234:235], v[230:233], off
	ds_read_b32 v230, v172 offset:96
	ds_read_b32 v231, v172 offset:356
	s_waitcnt lgkmcnt(0)
; #define LAS __attribute__((address_space(3)))
; #define KIN(i) ((const float*)karg(i))
; __device__ __forceinline__ unsigned pk2(float lo, float hi) { const bf16x2_t v = __builtin_convertvector((f32x2_t){lo, hi}, bf16x2_t); return __builtin_bit_cast(unsigned, v); }
; #define LDS_WAIT() asm volatile("s_waitcnt lgkmcnt(0)" ::: "memory")
; __device__ __forceinline__ void tr_store(const ItemD& d, int lane, const f32x4 (&v)[16], LAS float* scr) {
;     ...
;     for (int j = 0; j < 8; ++j) {
;         const int n = (lane >> 3) + 8 * j; const LAS float* s = scr + (8 * c) * 65 + n;
;         u32x4 o; o.x = pk2(s[0], s[65]); o.y = pk2(s[130], s[195]); o.z = pk2(s[260], s[325]); o.w = pk2(s[390], s[455]);
;         *(u32x4*)(d.WT + (size_t)n * d.ldt + 8 * c) = o;
;     }
;     LDS_WAIT();
; }
; __device__ __forceinline__ ItemD decode_item(int it) {
;     unsigned char* ws = KWS;
;     int r = it;
;     if (r < I_IN) { const int kb = r >> 7, nb = r & 127, n0 = nb * 64, seg = n0 >> 11; const int dseg = seg == 2 ? 3 : (seg == 3 ? 2 : seg);
;         return mk_item(KIN(5), 8192, kb * 64, n0, (bf16_t*)(ws + WS_WIN), DM, dseg * 2048 + (n0 & 2047)); }
;     r -= I_IN;
;     if (r < I_OUT) { const int kb = r >> 6, nb = r & 63; return mk_item(KIN(9), DM, kb * 64, nb * 64, (bf16_t*)(ws + WS_WOUT), DM, nb * 64); }
;     r -= I_OUT;
;     if (r < 2 * I_G) { const int up = r >= I_G; if (up) r -= I_G; const int kb = r / 172, nb = r % 172, n0 = nb * 64;
;         return mk_item(KIN(up ? 13 : 12), DFF, kb * 64, n0, (bf16_t*)(ws + WS_WGU), DM, (n0 >> 7) * 256 + (n0 & 127) + (up ? 128 : 0)); }
;     r -= 2 * I_G;
;     if (r < I_DN) { const int kb = r >> 6, nb = r & 63; return mk_item(KIN(14), DM, kb * 64, nb * 64, (bf16_t*)(ws + WS_WDOWN), DFF, nb * 64); }
;     r -= I_DN;
;     { const int g = r >> 6, rr = r & 63, kb = rr >> 3, nb = rr & 7;
;       return mk_item(KIN(7) + (size_t)g * 512 * 512, 512, kb * 64, nb * 64, (bf16_t*)(ws + WS_WPOOL) + (size_t)g * 512 * 512, 512, nb * 64); }
	v_cvt_pk_bf16_f32 v230, v230, v231
	ds_read_b32 v231, v172 offset:616
	ds_read_b32 v232, v172 offset:876
	s_waitcnt lgkmcnt(0)
	v_cvt_pk_bf16_f32 v231, v231, v232
	ds_read_b32 v232, v172 offset:1136
	ds_read_b32 v233, v172 offset:1396
	s_waitcnt lgkmcnt(0)
	v_cvt_pk_bf16_f32 v232, v232, v233
	ds_read_b32 v233, v172 offset:1656
	ds_read_b32 v234, v172 offset:1916
	s_waitcnt lgkmcnt(0)
	v_cvt_pk_bf16_f32 v233, v233, v234
	v_mad_u64_u32 v[234:235], s[74:75], s5, v140, 0
	v_mov_b32_e32 v236, v235
	v_mad_u64_u32 v[236:237], s[74:75], s5, v137, v[236:237]
	v_mov_b32_e32 v235, v236
	v_lshl_add_u64 v[234:235], v[234:235], 1, v[168:169]
	global_store_dwordx4 v[234:235], v[230:233], off
	ds_read_b32 v230, v172 offset:128
	ds_read_b32 v231, v172 offset:388
	s_waitcnt lgkmcnt(0)
	v_cvt_pk_bf16_f32 v230, v230, v231
	ds_read_b32 v231, v172 offset:648
	ds_read_b32 v232, v172 offset:908
	s_waitcnt lgkmcnt(0)
	v_cvt_pk_bf16_f32 v231, v231, v232
	ds_read_b32 v232, v172 offset:1168
	ds_read_b32 v233, v172 offset:1428
	s_waitcnt lgkmcnt(0)
	v_cvt_pk_bf16_f32 v232, v232, v233
	ds_read_b32 v233, v172 offset:1688
	ds_read_b32 v234, v172 offset:1948
	s_waitcnt lgkmcnt(0)
	v_cvt_pk_bf16_f32 v233, v233, v234
	v_mad_u64_u32 v[234:235], s[74:75], s5, v142, 0
	v_mov_b32_e32 v236, v235
	v_mad_u64_u32 v[236:237], s[74:75], s5, v139, v[236:237]
	v_mov_b32_e32 v235, v236
	v_lshl_add_u64 v[234:235], v[234:235], 1, v[168:169]
	global_store_dwordx4 v[234:235], v[230:233], off
	ds_read_b32 v230, v172 offset:160
	ds_read_b32 v231, v172 offset:420
	s_waitcnt lgkmcnt(0)
	v_cvt_pk_bf16_f32 v230, v230, v231
	ds_read_b32 v231, v172 offset:680
	ds_read_b32 v232, v172 offset:940
	s_waitcnt lgkmcnt(0)
	v_cvt_pk_bf16_f32 v231, v231, v232
	ds_read_b32 v232, v172 offset:1200
	ds_read_b32 v233, v172 offset:1460
	s_waitcnt lgkmcnt(0)
	v_cvt_pk_bf16_f32 v232, v232, v233
	ds_read_b32 v233, v172 offset:1720
	ds_read_b32 v234, v172 offset:1980
	s_waitcnt lgkmcnt(0)
	v_cvt_pk_bf16_f32 v233, v233, v234
	v_mad_u64_u32 v[234:235], s[74:75], s5, v162, 0
	v_mov_b32_e32 v236, v235
	v_mad_u64_u32 v[236:237], s[74:75], s5, v141, v[236:237]
	v_mov_b32_e32 v235, v236
	v_lshl_add_u64 v[234:235], v[234:235], 1, v[168:169]
	global_store_dwordx4 v[234:235], v[230:233], off
	ds_read_b32 v230, v172 offset:192
	ds_read_b32 v231, v172 offset:452
	s_waitcnt lgkmcnt(0)
	v_cvt_pk_bf16_f32 v230, v230, v231
	ds_read_b32 v231, v172 offset:712
	ds_read_b32 v232, v172 offset:972
	s_waitcnt lgkmcnt(0)
	v_cvt_pk_bf16_f32 v231, v231, v232
	ds_read_b32 v232, v172 offset:1232
	ds_read_b32 v233, v172 offset:1492
	s_waitcnt lgkmcnt(0)
	v_cvt_pk_bf16_f32 v232, v232, v233
	ds_read_b32 v233, v172 offset:1752
	ds_read_b32 v234, v172 offset:2012
	s_waitcnt lgkmcnt(0)
	v_cvt_pk_bf16_f32 v233, v233, v234
	v_mad_u64_u32 v[234:235], s[74:75], s5, v164, 0
	v_mov_b32_e32 v236, v235
	v_mad_u64_u32 v[236:237], s[74:75], s5, v143, v[236:237]
	v_mov_b32_e32 v235, v236
	v_lshl_add_u64 v[234:235], v[234:235], 1, v[168:169]
	global_store_dwordx4 v[234:235], v[230:233], off
	ds_read_b32 v230, v172 offset:224
	ds_read_b32 v231, v172 offset:484
	s_waitcnt lgkmcnt(0)
	v_cvt_pk_bf16_f32 v230, v230, v231
	ds_read_b32 v231, v172 offset:744
	ds_read_b32 v232, v172 offset:1004
	s_waitcnt lgkmcnt(0)
	v_cvt_pk_bf16_f32 v231, v231, v232
	ds_read_b32 v232, v172 offset:1264
	ds_read_b32 v233, v172 offset:1524
	s_waitcnt lgkmcnt(0)
	v_cvt_pk_bf16_f32 v232, v232, v233
	ds_read_b32 v233, v172 offset:1784
	ds_read_b32 v234, v172 offset:2044
	s_waitcnt lgkmcnt(0)
	v_cvt_pk_bf16_f32 v233, v233, v234
	v_mad_u64_u32 v[234:235], s[74:75], s5, v166, 0
	v_mov_b32_e32 v236, v235
	v_mad_u64_u32 v[236:237], s[74:75], s5, v163, v[236:237]
	v_mov_b32_e32 v235, v236
	v_lshl_add_u64 v[168:169], v[234:235], 1, v[168:169]
	global_store_dwordx4 v[168:169], v[230:233], off
	s_waitcnt lgkmcnt(0)
	s_mov_b64 s[74:75], -1
	s_cbranch_vccnz .LBB0_465
	s_add_i32 s12, s84, s88
	s_add_i32 s82, s12, 0x1ffb
	s_cmp_gt_i32 s82, 0xb1ff
	s_cbranch_scc1 .Lcv2_skipA
	s_load_dwordx2 s[10:11], s[0:1], 0x90
	s_cmpk_gt_i32 s82, 0x1fff
	s_mov_b64 s[80:81], -1
	s_cbranch_scc0 .LBB0_499
	s_cmpk_gt_u32 s82, 0x2fff
	s_cbranch_scc0 .LBB0_496
	s_cmpk_gt_u32 s82, 0x85ff
	s_cbranch_scc0 .LBB0_493
	s_cmpk_gt_u32 s82, 0xb0ff
	s_mov_b64 s[78:79], -1
	s_cbranch_scc0 .LBB0_490
	s_load_dwordx2 s[72:73], s[0:1], 0x38
	s_add_i32 s12, s12, 0xffff6efb
	s_lshr_b32 s12, s12, 6
	s_lshl_b64 s[74:75], s[12:13], 20
	v_readlane_b32 s47, v250, 13
	s_waitcnt lgkmcnt(0)
	s_add_u32 s5, s72, s74
	s_addc_u32 s74, s73, s75
	s_add_i32 s72, s47, s39
	s_and_b32 s76, s72, 0x1c0
	s_add_i32 s72, s22, s94
	s_and_b32 s78, s72, 0x1c0
	s_lshl_b64 s[72:73], s[12:13], 19
	s_add_u32 s12, s10, s72
	s_addc_u32 s73, s11, s73
	s_add_u32 s72, s12, 0x12200000
	s_addc_u32 s73, s73, 0
	s_lshl_b32 s12, s76, 11
	s_add_u32 s5, s5, s12
	s_addc_u32 s12, s74, 0
	s_lshl_b32 s74, s78, 2
	s_add_u32 s74, s5, s74
	s_mov_b32 s77, s13
	s_addc_u32 s75, s12, 0
	s_lshl_b32 s12, s78, 9
	s_mov_b64 s[78:79], 0

; template <int NQT, bool MASK, class KL, class VL> ...
;     ...
;     {
;         bf16x8 kf[2][2][4];
; #pragma unroll
;         for (int p = 0; p < 2; ++p)
; #pragma unroll
;             for (int tt = 0; tt < 2; ++tt)
; #pragma unroll
;                 for (int ks = 0; ks < 4; ++ks) kf[p][tt][ks] = kl(p, tt, ks);
;         __builtin_amdgcn_sched_barrier(0);
; #pragma unroll
;         for (int p = 0; p < 2; ++p)
; #pragma unroll
;             for (int tt = 0; tt < 2; ++tt)
; #pragma unroll
;                 for (int qt = 0; qt < NQT; ++qt) {
;                     f32x4 a = (f32x4){0.f, 0.f, 0.f, 0.f};
; #pragma unroll
;                     for (int ks = 0; ks < 4; ++ks) a = __builtin_amdgcn_mfma_f32_16x16x32_bf16(kf[p][tt][ks], Qf[qt][ks], a, 0, 0, 0);
;                     S[p][tt][qt] = a;
;                 }
;     }
.LBB0_506:
	s_load_dwordx2 s[22:23], s[0:1], 0x10
	s_load_dwordx2 s[76:77], s[0:1], 0x18
	v_mov_b32_e32 v138, v72
	v_mov_b32_e32 v137, v73
	s_waitcnt lgkmcnt(0)
	s_add_u32 s22, s22, s74
	s_addc_u32 s23, s23, s75
	global_load_dwordx4 v[48:51], v120, s[22:23]
	global_load_dwordx4 v[84:87], v120, s[22:23] offset:16
	global_load_dwordx4 v[52:55], v120, s[22:23] offset:128
	global_load_dwordx4 v[92:95], v120, s[22:23] offset:144
	global_load_dwordx4 v[56:59], v120, s[22:23] offset:256
	global_load_dwordx4 v[126:129], v120, s[22:23] offset:272
	global_load_dwordx4 v[60:63], v120, s[22:23] offset:384
	global_load_dwordx4 v[130:133], v120, s[22:23] offset:400
	s_add_u32 s76, s22, s68
	s_addc_u32 s77, s23, 0
	global_load_dwordx4 v[64:67], v120, s[76:77]
	global_load_dwordx4 v[140:143], v120, s[76:77] offset:16
	global_load_dwordx4 v[68:71], v120, s[76:77] offset:128
	global_load_dwordx4 v[172:175], v120, s[76:77] offset:144
	global_load_dwordx4 v[72:75], v120, s[76:77] offset:256
	global_load_dwordx4 v[176:179], v120, s[76:77] offset:272
	global_load_dwordx4 v[76:79], v120, s[76:77] offset:384
	global_load_dwordx4 v[180:183], v120, s[76:77] offset:400
	s_add_u32 s76, s22, s69
	s_addc_u32 s77, s23, 0
	global_load_dwordx4 v[80:83], v120, s[76:77]
	global_load_dwordx4 v[184:187], v120, s[76:77] offset:16
	global_load_dwordx4 v[88:91], v120, s[76:77] offset:128
	global_load_dwordx4 v[188:191], v120, s[76:77] offset:144
	global_load_dwordx4 v[96:99], v120, s[76:77] offset:256
	global_load_dwordx4 v[218:221], v120, s[76:77] offset:272
	global_load_dwordx4 v[100:103], v120, s[76:77] offset:384
	global_load_dwordx4 v[222:225], v120, s[76:77] offset:400
	s_add_u32 s76, s22, s3
	s_addc_u32 s77, s23, 0
	global_load_dwordx4 v[104:107], v120, s[76:77]
	global_load_dwordx4 v[226:229], v120, s[76:77] offset:16
	global_load_dwordx4 v[108:111], v120, s[76:77] offset:128
	global_load_dwordx4 v[230:233], v120, s[76:77] offset:144
	global_load_dwordx4 v[112:115], v120, s[76:77] offset:256
	global_load_dwordx4 v[234:237], v120, s[76:77] offset:272
	global_load_dwordx4 v[122:125], v120, s[76:77] offset:384
	global_load_dwordx4 v[144:147], v120, s[76:77] offset:400
	s_load_dwordx2 s[76:77], s[0:1], 0x18
	s_waitcnt vmcnt(0)
	v_cvt_pk_bf16_f32 v48, v48, v49
	v_cvt_pk_bf16_f32 v49, v50, v51
	v_cvt_pk_bf16_f32 v50, v84, v85
	v_cvt_pk_bf16_f32 v51, v86, v87
	v_cvt_pk_bf16_f32 v52, v52, v53
	v_cvt_pk_bf16_f32 v53, v54, v55
	v_cvt_pk_bf16_f32 v54, v92, v93
	v_cvt_pk_bf16_f32 v55, v94, v95
	v_cvt_pk_bf16_f32 v56, v56, v57
	v_cvt_pk_bf16_f32 v57, v58, v59
	v_cvt_pk_bf16_f32 v58, v126, v127
	v_cvt_pk_bf16_f32 v59, v128, v129
	v_cvt_pk_bf16_f32 v60, v60, v61
	v_cvt_pk_bf16_f32 v61, v62, v63
	v_cvt_pk_bf16_f32 v62, v130, v131
	v_cvt_pk_bf16_f32 v63, v132, v133
	v_cvt_pk_bf16_f32 v64, v64, v65
	v_cvt_pk_bf16_f32 v65, v66, v67
	v_cvt_pk_bf16_f32 v66, v140, v141
	v_cvt_pk_bf16_f32 v67, v142, v143
	v_cvt_pk_bf16_f32 v68, v68, v69
	v_cvt_pk_bf16_f32 v69, v70, v71
	v_cvt_pk_bf16_f32 v70, v172, v173
	v_cvt_pk_bf16_f32 v71, v174, v175
	v_cvt_pk_bf16_f32 v72, v72, v73
	v_cvt_pk_bf16_f32 v73, v74, v75
	v_cvt_pk_bf16_f32 v74, v176, v177
	v_cvt_pk_bf16_f32 v75, v178, v179
	v_cvt_pk_bf16_f32 v76, v76, v77
	v_cvt_pk_bf16_f32 v77, v78, v79
	v_cvt_pk_bf16_f32 v78, v180, v181
	v_cvt_pk_bf16_f32 v79, v182, v183
	v_cvt_pk_bf16_f32 v80, v80, v81
	v_cvt_pk_bf16_f32 v81, v82, v83
	v_cvt_pk_bf16_f32 v82, v184, v185
	v_cvt_pk_bf16_f32 v83, v186, v187
	v_cvt_pk_bf16_f32 v88, v88, v89
	v_cvt_pk_bf16_f32 v89, v90, v91
	v_cvt_pk_bf16_f32 v90, v188, v189
	v_cvt_pk_bf16_f32 v91, v190, v191
	v_cvt_pk_bf16_f32 v96, v96, v97
	v_cvt_pk_bf16_f32 v97, v98, v99
	v_cvt_pk_bf16_f32 v98, v218, v219
	v_cvt_pk_bf16_f32 v99, v220, v221
	v_cvt_pk_bf16_f32 v100, v100, v101
	v_cvt_pk_bf16_f32 v101, v102, v103
	v_cvt_pk_bf16_f32 v102, v222, v223
	v_cvt_pk_bf16_f32 v103, v224, v225
	v_cvt_pk_bf16_f32 v104, v104, v105
	v_cvt_pk_bf16_f32 v105, v106, v107
	v_cvt_pk_bf16_f32 v106, v226, v227
	v_cvt_pk_bf16_f32 v107, v228, v229
	v_cvt_pk_bf16_f32 v108, v108, v109
	v_cvt_pk_bf16_f32 v109, v110, v111
	v_cvt_pk_bf16_f32 v110, v230, v231
	v_cvt_pk_bf16_f32 v111, v232, v233
	v_cvt_pk_bf16_f32 v112, v112, v113
	v_cvt_pk_bf16_f32 v113, v114, v115
	v_cvt_pk_bf16_f32 v114, v234, v235
	v_cvt_pk_bf16_f32 v115, v236, v237
	v_cvt_pk_bf16_f32 v122, v122, v123
	v_cvt_pk_bf16_f32 v123, v124, v125
	v_cvt_pk_bf16_f32 v124, v144, v145
	v_cvt_pk_bf16_f32 v125, v146, v147
	v_mfma_f32_16x16x32_bf16 v[48:51], v[48:51], v[32:35], 0
	v_mfma_f32_16x16x32_bf16 v[48:51], v[52:55], v[36:39], v[48:51]
	v_mfma_f32_16x16x32_bf16 v[48:51], v[56:59], v[40:43], v[48:51]
	v_mfma_f32_16x16x32_bf16 v[92:95], v[60:63], v[44:47], v[48:51]
	v_mfma_f32_16x16x32_bf16 v[48:51], v[64:67], v[32:35], 0
	v_mfma_f32_16x16x32_bf16 v[48:51], v[68:71], v[36:39], v[48:51]
	v_mfma_f32_16x16x32_bf16 v[48:51], v[72:75], v[40:43], v[48:51]
	v_mfma_f32_16x16x32_bf16 v[84:87], v[76:79], v[44:47], v[48:51]
	v_mfma_f32_16x16x32_bf16 v[48:51], v[80:83], v[32:35], 0
	v_mfma_f32_16x16x32_bf16 v[48:51], v[88:91], v[36:39], v[48:51]
	v_mfma_f32_16x16x32_bf16 v[48:51], v[96:99], v[40:43], v[48:51]
	v_mfma_f32_16x16x32_bf16 v[80:83], v[100:103], v[44:47], v[48:51]
	v_mfma_f32_16x16x32_bf16 v[48:51], v[104:107], v[32:35], 0
	v_mfma_f32_16x16x32_bf16 v[48:51], v[108:111], v[36:39], v[48:51]
	v_mfma_f32_16x16x32_bf16 v[48:51], v[112:115], v[40:43], v[48:51]
	v_mfma_f32_16x16x32_bf16 v[72:75], v[122:125], v[44:47], v[48:51]
	s_nop 6
	s_waitcnt lgkmcnt(0)
; template <int NQT, bool MASK, class KL, class VL> ...
;     ...
;     bf16x8 vfa[4][2], vfb[4][2];
; #pragma unroll
;     for (int dt = 0; dt < 4; ++dt)
; #pragma unroll
;         for (int p = 0; p < 2; ++p) vfa[dt][p] = vl(dt, p);
;     __builtin_amdgcn_sched_barrier(0);
;     bf16x8 Pf[NQT][2];
; #pragma unroll
;     for (int qt = 0; qt < NQT; ++qt) {
;         float mx = -1e30f;
; #pragma unroll
;         for (int p = 0; p < 2; ++p)
; #pragma unroll
;             for (int tt = 0; tt < 2; ++tt)
; #pragma unroll
;                 for (int r = 0; r < 4; ++r) {
;                     const int off = 32 * p + 4 * tt + r;
;                     int idx = dbase[qt] - off + 256; idx = idx < 0 ? 0 : (idx > 512 ? 512 : idx);
;                     float s = S[p][tt][qt][r] * sscale + btab[idx];
;                     if (MASK && off >= nv) s = -1e30f;
;                     S[p][tt][qt][r] = s; mx = fmaxf(mx, s);
	v_lshl_add_u64 v[48:49], s[76:77], 0, v[118:119]
	v_lshl_add_u64 v[96:97], v[48:49], 0, s[74:75]
	s_mov_b64 s[22:23], 0x2000
	v_lshl_add_u64 v[98:99], v[96:97], 0, s[22:23]
	s_mov_b64 s[22:23], 0x4000
	v_lshl_add_u64 v[100:101], v[96:97], 0, s[22:23]
	s_mov_b64 s[22:23], 0x6000
	v_lshl_add_u64 v[102:103], v[96:97], 0, s[22:23]
	s_mov_b64 s[22:23], 0x8000
	v_lshl_add_u64 v[104:105], v[96:97], 0, s[22:23]
	s_mov_b64 s[22:23], 0xa000
	v_lshl_add_u64 v[106:107], v[96:97], 0, s[22:23]
	s_mov_b64 s[22:23], 0xc000
	v_lshl_add_u64 v[108:109], v[96:97], 0, s[22:23]
	s_mov_b64 s[22:23], 0xe000
	v_lshl_add_u64 v[110:111], v[96:97], 0, s[22:23]
	s_mov_b64 s[22:23], 0x40000
	v_lshl_add_u64 v[112:113], v[96:97], 0, s[22:23]
	s_mov_b64 s[22:23], 0x42000
	v_lshl_add_u64 v[114:115], v[96:97], 0, s[22:23]
	s_mov_b64 s[22:23], 0x44000
	v_lshl_add_u64 v[122:123], v[96:97], 0, s[22:23]
	s_mov_b64 s[22:23], 0x46000
	v_lshl_add_u64 v[124:125], v[96:97], 0, s[22:23]
	s_mov_b64 s[22:23], 0x48000
	v_lshl_add_u64 v[126:127], v[96:97], 0, s[22:23]
	s_mov_b64 s[22:23], 0x4a000
	v_lshl_add_u64 v[128:129], v[96:97], 0, s[22:23]
	s_mov_b64 s[22:23], 0x4c000
	v_lshl_add_u64 v[130:131], v[96:97], 0, s[22:23]
	s_mov_b64 s[22:23], 0x4e000
	v_lshl_add_u64 v[132:133], v[96:97], 0, s[22:23]
	global_load_dword v48, v[96:97], off
	global_load_dword v49, v[98:99], off
	global_load_dword v50, v[100:101], off
	global_load_dword v51, v[102:103], off
	global_load_dword v172, v[104:105], off
	global_load_dword v173, v[106:107], off
	global_load_dword v174, v[108:109], off
	global_load_dword v175, v[110:111], off
	global_load_dword v52, v[112:113], off
	global_load_dword v53, v[114:115], off
	global_load_dword v54, v[122:123], off
	global_load_dword v55, v[124:125], off
	global_load_dword v176, v[126:127], off
	global_load_dword v177, v[128:129], off
	global_load_dword v178, v[130:131], off
	global_load_dword v179, v[132:133], off
	global_load_dword v56, v[96:97], off offset:64
	global_load_dword v57, v[98:99], off offset:64
	global_load_dword v58, v[100:101], off offset:64
	global_load_dword v59, v[102:103], off offset:64
	global_load_dword v180, v[104:105], off offset:64
	global_load_dword v181, v[106:107], off offset:64
	global_load_dword v182, v[108:109], off offset:64
	global_load_dword v183, v[110:111], off offset:64
	global_load_dword v60, v[112:113], off offset:64
	global_load_dword v61, v[114:115], off offset:64
	global_load_dword v62, v[122:123], off offset:64
	global_load_dword v63, v[124:125], off offset:64
	global_load_dword v184, v[126:127], off offset:64
	global_load_dword v185, v[128:129], off offset:64
	global_load_dword v186, v[130:131], off offset:64
	global_load_dword v187, v[132:133], off offset:64
	global_load_dword v64, v[96:97], off offset:128
	global_load_dword v65, v[98:99], off offset:128
	global_load_dword v66, v[100:101], off offset:128
	global_load_dword v67, v[102:103], off offset:128
	global_load_dword v188, v[104:105], off offset:128
	global_load_dword v189, v[106:107], off offset:128
	global_load_dword v190, v[108:109], off offset:128
	global_load_dword v191, v[110:111], off offset:128
	global_load_dword v68, v[112:113], off offset:128
	global_load_dword v69, v[114:115], off offset:128
	global_load_dword v70, v[122:123], off offset:128
	global_load_dword v71, v[124:125], off offset:128
	global_load_dword v218, v[126:127], off offset:128
	global_load_dword v219, v[128:129], off offset:128
	global_load_dword v220, v[130:131], off offset:128
	global_load_dword v221, v[132:133], off offset:128
	global_load_dword v76, v[96:97], off offset:192
	global_load_dword v77, v[98:99], off offset:192
	global_load_dword v78, v[100:101], off offset:192
	global_load_dword v79, v[102:103], off offset:192
	global_load_dword v222, v[104:105], off offset:192
	global_load_dword v223, v[106:107], off offset:192
	global_load_dword v224, v[108:109], off offset:192
	global_load_dword v225, v[110:111], off offset:192
	global_load_dword v88, v[112:113], off offset:192
	global_load_dword v89, v[114:115], off offset:192
	global_load_dword v90, v[122:123], off offset:192
	global_load_dword v91, v[124:125], off offset:192
	global_load_dword v226, v[126:127], off offset:192
	global_load_dword v227, v[128:129], off offset:192
	global_load_dword v228, v[130:131], off offset:192
	global_load_dword v229, v[132:133], off offset:192
	s_waitcnt vmcnt(0)
	v_cvt_pk_bf16_f32 v48, v48, v49
	v_cvt_pk_bf16_f32 v49, v50, v51
	v_cvt_pk_bf16_f32 v50, v172, v173
	v_cvt_pk_bf16_f32 v51, v174, v175
	v_cvt_pk_bf16_f32 v52, v52, v53
	v_cvt_pk_bf16_f32 v53, v54, v55
	v_cvt_pk_bf16_f32 v54, v176, v177
	v_cvt_pk_bf16_f32 v55, v178, v179
	v_cvt_pk_bf16_f32 v56, v56, v57
	v_cvt_pk_bf16_f32 v57, v58, v59
	v_cvt_pk_bf16_f32 v58, v180, v181
	v_cvt_pk_bf16_f32 v59, v182, v183
	v_cvt_pk_bf16_f32 v60, v60, v61
	v_cvt_pk_bf16_f32 v61, v62, v63
	v_cvt_pk_bf16_f32 v62, v184, v185
	v_cvt_pk_bf16_f32 v63, v186, v187
	v_cvt_pk_bf16_f32 v64, v64, v65
	v_cvt_pk_bf16_f32 v65, v66, v67
	v_cvt_pk_bf16_f32 v66, v188, v189
	v_cvt_pk_bf16_f32 v67, v190, v191
	v_cvt_pk_bf16_f32 v68, v68, v69
	v_cvt_pk_bf16_f32 v69, v70, v71
	v_cvt_pk_bf16_f32 v70, v218, v219
	v_cvt_pk_bf16_f32 v71, v220, v221
	v_cvt_pk_bf16_f32 v76, v76, v77
	v_cvt_pk_bf16_f32 v77, v78, v79
	v_cvt_pk_bf16_f32 v78, v222, v223
	v_cvt_pk_bf16_f32 v79, v224, v225
	v_cvt_pk_bf16_f32 v88, v88, v89
	v_cvt_pk_bf16_f32 v89, v90, v91
	v_cvt_pk_bf16_f32 v90, v226, v227
	v_cvt_pk_bf16_f32 v91, v228, v229
	v_add_u32_e32 v140, -2, v117
	v_med3_i32 v139, v117, s26, v201
	v_med3_i32 v140, v140, s26, v201
	v_lshl_add_u32 v139, v139, 2, 0
	v_lshl_add_u32 v140, v140, 2, 0
	ds_read_b32 v139, v139 offset:3136
	ds_read_b32 v140, v140 offset:3136
	s_waitcnt lgkmcnt(1)
; __device__ __forceinline__ unsigned pk2(float lo, float hi) { const bf16x2_t v = __builtin_convertvector((f32x2_t){lo, hi}, bf16x2_t); return __builtin_bit_cast(unsigned, v); }
; template <int NQT, bool MASK, class KL, class VL> ...
;     ...
; #pragma unroll
;     for (int qt = 0; qt < NQT; ++qt) {
;         float mx = -1e30f;
; #pragma unroll
;         for (int p = 0; p < 2; ++p)
; #pragma unroll
;             for (int tt = 0; tt < 2; ++tt)
; #pragma unroll
;                 for (int r = 0; r < 4; ++r) {
;                     const int off = 32 * p + 4 * tt + r;
;                     int idx = dbase[qt] - off + 256; idx = idx < 0 ? 0 : (idx > 512 ? 512 : idx);
;                     float s = S[p][tt][qt][r] * sscale + btab[idx];
;                     if (MASK && off >= nv) s = -1e30f;
;                     S[p][tt][qt][r] = s; mx = fmaxf(mx, s);
;                 }
;         mx = fmaxf(mx, __shfl_xor(mx, 16)); mx = fmaxf(mx, __shfl_xor(mx, 32));
;         const float mn = fmaxf(mrow[qt], mx), alpha = __builtin_amdgcn_exp2f(mrow[qt] - mn); mrow[qt] = mn;
;         float ls = 0.f;
; #pragma unroll
;         for (int p = 0; p < 2; ++p)
; #pragma unroll
;             for (int tt = 0; tt < 2; ++tt)
; #pragma unroll
;                 for (int r = 0; r < 4; ++r) { const float pv = __builtin_amdgcn_exp2f(S[p][tt][qt][r] - mn); S[p][tt][qt][r] = pv; ls += pv; }
;         lrow[qt] = lrow[qt] * alpha + ls;
; #pragma unroll
;         for (int dt = 0; dt < 8; ++dt) O[qt][dt] *= alpha;
; #pragma unroll
;         for (int p = 0; p < 2; ++p) {
;             u32x4 w; w.x = pk2(S[p][0][qt][0], S[p][0][qt][1]); w.y = pk2(S[p][0][qt][2], S[p][0][qt][3]); w.z = pk2(S[p][1][qt][0], S[p][1][qt][1]); w.w = pk2(S[p][1][qt][2], S[p][1][qt][3]);
;             Pf[qt][p] = __builtin_bit_cast(bf16x8, w);
;         }
;     }
	v_fmac_f32_e32 v139, 0x3e0293ee, v92
	v_add_u32_e32 v92, -1, v117
	s_waitcnt lgkmcnt(0)
	v_fmac_f32_e32 v140, 0x3e0293ee, v94
	v_add_u32_e32 v94, -3, v117
	v_med3_i32 v92, v92, s26, v201
	v_med3_i32 v94, v94, s26, v201
	v_lshl_add_u32 v92, v92, 2, 0
	v_lshl_add_u32 v94, v94, 2, 0
	ds_read_b32 v92, v92 offset:3136
	ds_read_b32 v94, v94 offset:3136
	s_waitcnt lgkmcnt(0)
	v_fmac_f32_e32 v94, 0x3e0293ee, v95
	v_add_u32_e32 v95, -4, v117
	v_med3_i32 v95, v95, s26, v201
	v_lshl_add_u32 v95, v95, 2, 0
	ds_read_b32 v95, v95 offset:3136
	s_waitcnt lgkmcnt(0)
	v_fmac_f32_e32 v95, 0x3e0293ee, v84
	v_add_u32_e32 v84, -5, v117
	v_med3_i32 v84, v84, s26, v201
	v_lshl_add_u32 v84, v84, 2, 0
	ds_read_b32 v84, v84 offset:3136
	v_fmac_f32_e32 v92, 0x3e0293ee, v93
	v_max3_f32 v93, v139, s27, v92
	v_max3_f32 v93, v93, v140, v94
	s_waitcnt lgkmcnt(0)
	v_fmac_f32_e32 v84, 0x3e0293ee, v85
	v_max3_f32 v85, v93, v95, v84
	v_add_u32_e32 v93, -6, v117
	v_med3_i32 v93, v93, s26, v201
	v_lshl_add_u32 v93, v93, 2, 0
	ds_read_b32 v93, v93 offset:3136
	s_waitcnt lgkmcnt(0)
	v_fmac_f32_e32 v93, 0x3e0293ee, v86
	v_add_u32_e32 v86, -7, v117
	v_med3_i32 v86, v86, s26, v201
	v_lshl_add_u32 v86, v86, 2, 0
	ds_read_b32 v86, v86 offset:3136
	s_waitcnt lgkmcnt(0)
	v_fmac_f32_e32 v86, 0x3e0293ee, v87
	v_subrev_u32_e32 v87, 32, v117
	v_med3_i32 v87, v87, s26, v201
	v_lshl_add_u32 v87, v87, 2, 0
	ds_read_b32 v87, v87 offset:3136
	v_max3_f32 v85, v85, v93, v86
	s_waitcnt lgkmcnt(0)
	v_fmac_f32_e32 v87, 0x3e0293ee, v80
	v_subrev_u32_e32 v80, 33, v117
	v_med3_i32 v80, v80, s26, v201
	v_lshl_add_u32 v80, v80, 2, 0
	ds_read_b32 v80, v80 offset:3136
	s_waitcnt lgkmcnt(0)
	v_fmac_f32_e32 v80, 0x3e0293ee, v81
	v_max3_f32 v81, v85, v87, v80
	v_subrev_u32_e32 v85, 34, v117
	v_med3_i32 v85, v85, s26, v201
	v_lshl_add_u32 v85, v85, 2, 0
	ds_read_b32 v85, v85 offset:3136
	s_waitcnt lgkmcnt(0)
	v_fmac_f32_e32 v85, 0x3e0293ee, v82
	v_subrev_u32_e32 v82, 35, v117
	v_med3_i32 v82, v82, s26, v201
	v_lshl_add_u32 v82, v82, 2, 0
	ds_read_b32 v82, v82 offset:3136
	s_waitcnt lgkmcnt(0)
	v_fmac_f32_e32 v82, 0x3e0293ee, v83
	v_subrev_u32_e32 v83, 36, v117
	v_med3_i32 v83, v83, s26, v201
	v_lshl_add_u32 v83, v83, 2, 0
	ds_read_b32 v83, v83 offset:3136
	v_max3_f32 v81, v81, v85, v82
	s_waitcnt lgkmcnt(0)
	v_fmac_f32_e32 v83, 0x3e0293ee, v72
	v_subrev_u32_e32 v72, 37, v117
	v_med3_i32 v72, v72, s26, v201
	v_lshl_add_u32 v72, v72, 2, 0
	ds_read_b32 v141, v72 offset:3136
	s_waitcnt lgkmcnt(0)
	v_fmac_f32_e32 v141, 0x3e0293ee, v73
	v_subrev_u32_e32 v73, 38, v117
	v_med3_i32 v73, v73, s26, v201
	v_lshl_add_u32 v73, v73, 2, 0
	ds_read_b32 v73, v73 offset:3136
	v_max3_f32 v72, v81, v83, v141
	s_waitcnt lgkmcnt(0)
	v_fmac_f32_e32 v73, 0x3e0293ee, v74
	v_subrev_u32_e32 v74, 39, v117
	v_med3_i32 v74, v74, s26, v201
	v_lshl_add_u32 v74, v74, 2, 0
	ds_read_b32 v74, v74 offset:3136
	s_waitcnt lgkmcnt(0)
	v_fmac_f32_e32 v74, 0x3e0293ee, v75
	v_max3_f32 v72, v72, v73, v74
	ds_bpermute_b32 v75, v135, v72
	s_waitcnt lgkmcnt(0)
	v_max_f32_e32 v75, v75, v75
	v_max_f32_e32 v72, v72, v75
	ds_bpermute_b32 v75, v134, v72
	s_waitcnt lgkmcnt(0)
	v_max3_f32 v72, v138, v72, v75
	v_sub_f32_e32 v81, v139, v72
	v_sub_f32_e32 v75, v138, v72
	v_exp_f32_e32 v138, v81
	v_sub_f32_e32 v92, v92, v72
	v_exp_f32_e32 v92, v92
	v_sub_f32_e32 v139, v140, v72
	v_exp_f32_e32 v139, v139
	v_sub_f32_e32 v94, v94, v72
	v_exp_f32_e32 v94, v94
	v_sub_f32_e32 v95, v95, v72
	v_add_f32_e32 v81, 0, v138
	v_exp_f32_e32 v95, v95
	v_sub_f32_e32 v84, v84, v72
	v_add_f32_e32 v81, v92, v81
	v_exp_f32_e32 v140, v84
	v_sub_f32_e32 v84, v93, v72
	v_add_f32_e32 v81, v139, v81
	v_exp_f32_e32 v93, v84
	v_sub_f32_e32 v84, v86, v72
	v_add_f32_e32 v81, v94, v81
	v_exp_f32_e32 v142, v84
	v_sub_f32_e32 v84, v87, v72
	v_add_f32_e32 v81, v95, v81
	v_exp_f32_e32 v143, v84
	v_sub_f32_e32 v80, v80, v72
	v_add_f32_e32 v81, v140, v81
	v_exp_f32_e32 v160, v80
	v_add_f32_e32 v81, v93, v81
	v_add_f32_e32 v81, v142, v81
	v_add_f32_e32 v81, v143, v81
	v_add_f32_e32 v80, v160, v81
	v_sub_f32_e32 v81, v85, v72
	v_exp_f32_e32 v162, v81
	v_sub_f32_e32 v81, v82, v72
	v_exp_f32_e32 v163, v81
	v_sub_f32_e32 v81, v83, v72
	v_exp_f32_e32 v164, v81
	v_sub_f32_e32 v81, v141, v72
	v_exp_f32_e32 v141, v81
	v_sub_f32_e32 v73, v73, v72
	v_add_f32_e32 v80, v162, v80
	v_exp_f32_e32 v166, v73
	v_sub_f32_e32 v74, v74, v72
	v_add_f32_e32 v80, v163, v80
	v_exp_f32_e32 v168, v74
	v_add_f32_e32 v80, v164, v80
	v_exp_f32_e32 v74, v75
	v_add_f32_e32 v80, v141, v80
	v_add_f32_e32 v73, v166, v80
	v_add_f32_e32 v73, v168, v73
	v_fmac_f32_e32 v73, v137, v74
	v_pk_mul_f32 v[30:31], v[30:31], v[74:75] op_sel_hi:[1,0]
	v_pk_mul_f32 v[28:29], v[28:29], v[74:75] op_sel_hi:[1,0]
	v_pk_mul_f32 v[26:27], v[26:27], v[74:75] op_sel_hi:[1,0]
	v_pk_mul_f32 v[24:25], v[24:25], v[74:75] op_sel_hi:[1,0]
	v_pk_mul_f32 v[22:23], v[22:23], v[74:75] op_sel_hi:[1,0]
	v_pk_mul_f32 v[20:21], v[20:21], v[74:75] op_sel_hi:[1,0]
	v_pk_mul_f32 v[18:19], v[18:19], v[74:75] op_sel_hi:[1,0]
	v_pk_mul_f32 v[16:17], v[16:17], v[74:75] op_sel_hi:[1,0]
	v_pk_mul_f32 v[10:11], v[10:11], v[74:75] op_sel_hi:[1,0]
	v_pk_mul_f32 v[8:9], v[8:9], v[74:75] op_sel_hi:[1,0]
	v_pk_mul_f32 v[6:7], v[6:7], v[74:75] op_sel_hi:[1,0]
	v_pk_mul_f32 v[4:5], v[4:5], v[74:75] op_sel_hi:[1,0]
	v_pk_mul_f32 v[2:3], v[2:3], v[74:75] op_sel_hi:[1,0]
	v_pk_mul_f32 v[0:1], v[0:1], v[74:75] op_sel_hi:[1,0]
	v_pk_mul_f32 v[82:83], v[14:15], v[74:75] op_sel_hi:[1,0]
	v_pk_mul_f32 v[80:81], v[12:13], v[74:75] op_sel_hi:[1,0]
	v_cvt_pk_bf16_f32 v12, v143, v160
	v_cvt_pk_bf16_f32 v13, v162, v163
	v_cvt_pk_bf16_f32 v14, v164, v141
	v_cvt_pk_bf16_f32 v15, v166, v168
; #define KIN(i) ((const float*)karg(i))
; template <int NQT, bool MASK, class KL, class VL> ...
;     ...
;     __builtin_amdgcn_sched_barrier(0);
; #pragma unroll
;     for (int dt = 0; dt < 4; ++dt)
; #pragma unroll
;         for (int p = 0; p < 2; ++p) vfb[dt][p] = vl(dt + 4, p);
;     __builtin_amdgcn_sched_barrier(0);
; #pragma unroll
;     for (int dt = 0; dt < 4; ++dt)
; #pragma unroll
;         for (int p = 0; p < 2; ++p)
; #pragma unroll
;             for (int qt = 0; qt < NQT; ++qt) O[qt][dt] = __builtin_amdgcn_mfma_f32_16x16x32_bf16(vfa[dt][p], Pf[qt][p], O[qt][dt], 0, 0, 0);
; #pragma unroll
;     for (int dt = 0; dt < 4; ++dt)
; #pragma unroll
;         for (int p = 0; p < 2; ++p)
; #pragma unroll
;             for (int qt = 0; qt < NQT; ++qt) O[qt][dt + 4] = __builtin_amdgcn_mfma_f32_16x16x32_bf16(vfb[dt][p], Pf[qt][p], O[qt][dt + 4], 0, 0, 0);
; __device__ __forceinline__ void phase2(LAS unsigned char* lds, int wave) {
;     ...
;             for (int kt = 0; kt < 8; ++kt) {
;                 const int key0 = 64 * kt;
;                 KLoadF32 kl{KIN(2) + ((size_t)(b * 512 + key0) * 16 + h) * DH, (unsigned)(krow * 2048 + g * 8)};
;                 VLoadF32 vl{KIN(3) + ((size_t)(b * 512 + key0) * 16 + h) * DH, (unsigned)(8 * g * 2048 + r)};
;                 const int dbase[1] = {512 + r - key0 - 8 * g};
;                 attn_tile<1, false>(Qf, O, mrow, lrow, kl, vl, btS, dbase, 64, sscale);
;             }
	v_cvt_pk_bf16_f32 v84, v138, v92
	v_cvt_pk_bf16_f32 v85, v139, v94
	v_cvt_pk_bf16_f32 v86, v95, v140
	v_cvt_pk_bf16_f32 v87, v93, v142
	flat_load_dword v74, v[96:97] offset:256
	flat_load_dword v75, v[98:99] offset:256
	flat_load_dword v137, v[96:97] offset:320
	flat_load_dword v138, v[98:99] offset:320
	flat_load_dword v93, v[100:101] offset:256
	flat_load_dword v94, v[102:103] offset:256
	flat_load_dword v139, v[100:101] offset:320
	flat_load_dword v140, v[102:103] offset:320
	flat_load_dword v95, v[104:105] offset:256
	flat_load_dword v141, v[106:107] offset:256
	flat_load_dword v142, v[104:105] offset:320
	flat_load_dword v143, v[106:107] offset:320
	flat_load_dword v160, v[104:105] offset:384
	flat_load_dword v162, v[106:107] offset:384
	flat_load_dword v163, v[108:109] offset:256
	flat_load_dword v164, v[110:111] offset:256
	flat_load_dword v166, v[108:109] offset:320
	flat_load_dword v168, v[110:111] offset:320
	flat_load_dword v169, v[108:109] offset:384
	flat_load_dword v171, v[110:111] offset:384
	flat_load_dword v172, v[112:113] offset:256
	flat_load_dword v173, v[114:115] offset:256
	flat_load_dword v174, v[112:113] offset:320
	flat_load_dword v175, v[114:115] offset:320
	flat_load_dword v176, v[112:113] offset:384
	flat_load_dword v177, v[114:115] offset:384
	flat_load_dword v178, v[122:123] offset:256
	flat_load_dword v179, v[124:125] offset:256
	flat_load_dword v180, v[122:123] offset:320
	flat_load_dword v181, v[124:125] offset:320
	flat_load_dword v182, v[122:123] offset:384
	flat_load_dword v183, v[124:125] offset:384
	flat_load_dword v184, v[126:127] offset:256
	flat_load_dword v185, v[128:129] offset:256
	flat_load_dword v186, v[126:127] offset:320
	flat_load_dword v187, v[128:129] offset:320
	flat_load_dword v188, v[126:127] offset:384
	flat_load_dword v189, v[128:129] offset:384
	flat_load_dword v190, v[130:131] offset:256
	flat_load_dword v191, v[132:133] offset:256
	flat_load_dword v218, v[130:131] offset:320
	flat_load_dword v219, v[132:133] offset:320
	flat_load_dword v220, v[130:131] offset:384
	flat_load_dword v221, v[132:133] offset:384
	flat_load_dword v222, v[96:97] offset:384
	flat_load_dword v223, v[98:99] offset:384
	flat_load_dword v224, v[98:99] offset:448
	flat_load_dword v225, v[96:97] offset:448
	flat_load_dword v226, v[100:101] offset:384
	flat_load_dword v227, v[102:103] offset:384
	flat_load_dword v228, v[102:103] offset:448
	flat_load_dword v229, v[100:101] offset:448
	flat_load_dword v230, v[106:107] offset:448
	flat_load_dword v231, v[104:105] offset:448
	flat_load_dword v232, v[110:111] offset:448
	flat_load_dword v233, v[108:109] offset:448
	flat_load_dword v234, v[114:115] offset:448
	flat_load_dword v235, v[112:113] offset:448
	flat_load_dword v236, v[124:125] offset:448
	flat_load_dword v237, v[122:123] offset:448
	s_nop 0
	flat_load_dword v128, v[128:129] offset:448
	s_nop 0
	flat_load_dword v129, v[126:127] offset:448
	s_nop 0
	flat_load_dword v132, v[132:133] offset:448
	s_nop 0
	flat_load_dword v130, v[130:131] offset:448
	s_waitcnt vmcnt(0) lgkmcnt(0)
	v_cvt_pk_bf16_f32 v92, v74, v75
	v_cvt_pk_bf16_f32 v100, v137, v138
	v_cvt_pk_bf16_f32 v93, v93, v94
	v_cvt_pk_bf16_f32 v101, v139, v140
	v_cvt_pk_bf16_f32 v94, v95, v141
	v_cvt_pk_bf16_f32 v102, v142, v143
	v_cvt_pk_bf16_f32 v110, v160, v162
	v_cvt_pk_bf16_f32 v95, v163, v164
	v_cvt_pk_bf16_f32 v103, v166, v168
	v_cvt_pk_bf16_f32 v111, v169, v171
	v_cvt_pk_bf16_f32 v96, v172, v173
	v_cvt_pk_bf16_f32 v104, v174, v175
	v_cvt_pk_bf16_f32 v112, v176, v177
	v_cvt_pk_bf16_f32 v97, v178, v179
	v_cvt_pk_bf16_f32 v105, v180, v181
	v_cvt_pk_bf16_f32 v113, v182, v183
	v_cvt_pk_bf16_f32 v98, v184, v185
	v_cvt_pk_bf16_f32 v106, v186, v187
	v_cvt_pk_bf16_f32 v114, v188, v189
	v_cvt_pk_bf16_f32 v99, v190, v191
	v_cvt_pk_bf16_f32 v107, v218, v219
	v_cvt_pk_bf16_f32 v115, v220, v221
	v_cvt_pk_bf16_f32 v108, v222, v223
	v_cvt_pk_bf16_f32 v122, v225, v224
	v_cvt_pk_bf16_f32 v109, v226, v227
	v_cvt_pk_bf16_f32 v123, v229, v228
	v_cvt_pk_bf16_f32 v124, v231, v230
	v_cvt_pk_bf16_f32 v125, v233, v232
	v_cvt_pk_bf16_f32 v126, v235, v234
	v_cvt_pk_bf16_f32 v127, v237, v236
	v_cvt_pk_bf16_f32 v128, v129, v128
	v_cvt_pk_bf16_f32 v129, v130, v132
	v_mfma_f32_16x16x32_bf16 v[28:31], v[48:51], v[84:87], v[28:31]
	s_add_u32 s74, s74, 0x80000
	s_addc_u32 s75, s75, 0
	v_subrev_u32_e32 v117, 64, v117
	v_mfma_f32_16x16x32_bf16 v[24:27], v[56:59], v[84:87], v[24:27]
	s_cmp_eq_u32 s74, 0x400000
	v_mfma_f32_16x16x32_bf16 v[20:23], v[64:67], v[84:87], v[20:23]
	v_mfma_f32_16x16x32_bf16 v[16:19], v[76:79], v[84:87], v[16:19]
	v_mfma_f32_16x16x32_bf16 v[8:11], v[92:95], v[84:87], v[8:11]
	v_mfma_f32_16x16x32_bf16 v[4:7], v[100:103], v[84:87], v[4:7]
	v_mfma_f32_16x16x32_bf16 v[0:3], v[108:111], v[84:87], v[0:3]
	v_mfma_f32_16x16x32_bf16 v[48:51], v[122:125], v[84:87], v[80:83]
	v_mfma_f32_16x16x32_bf16 v[28:31], v[52:55], v[12:15], v[28:31]
	v_mfma_f32_16x16x32_bf16 v[24:27], v[60:63], v[12:15], v[24:27]
	v_mfma_f32_16x16x32_bf16 v[20:23], v[68:71], v[12:15], v[20:23]
	v_mfma_f32_16x16x32_bf16 v[16:19], v[88:91], v[12:15], v[16:19]
	v_mfma_f32_16x16x32_bf16 v[8:11], v[96:99], v[12:15], v[8:11]
	v_mfma_f32_16x16x32_bf16 v[4:7], v[104:107], v[12:15], v[4:7]
	v_mfma_f32_16x16x32_bf16 v[0:3], v[112:115], v[12:15], v[0:3]
	v_mfma_f32_16x16x32_bf16 v[12:15], v[126:129], v[12:15], v[48:51]
	s_cbranch_scc0 .LBB0_506
; __device__ __forceinline__ void phase2(LAS unsigned char* lds, int wave) {
;     ...
;             {
;                 KLoadNew kl{Kb + (size_t)(NPROMPT + b * 16) * 2048 + h * DH + g * 8, krow};
;                 VLoadNew vl{VT + (size_t)(h * DH + r) * NTOK + NPROMPT + b * 16 + 8 * (g & 1), g};
;                 const int dbase[1] = {r - 8 * g};
;                 attn_tile<1, true>(Qf, O, mrow, lrow, kl, vl, btS, dbase, 16 - 8 * g, sscale);
;             }
	s_add_u32 s11, s85, s14
	s_addc_u32 s12, s86, s15
	s_lshl_b32 s4, s5, 1
	s_add_u32 s14, s11, s4
	s_addc_u32 s15, s12, 0
	v_ashrrev_i32_e32 v117, 31, v116
	v_add_u32_e32 v50, s5, v165
	v_mov_b64_e32 v[48:49], s[66:67]
	s_movk_i32 s5, 0x4200
	v_lshl_add_u64 v[70:71], v[116:117], 1, s[14:15]
	v_mad_i64_i32 v[48:49], s[14:15], v50, s5, v[48:49]
	s_ashr_i32 s11, s10, 31
	v_and_b32_e32 v50, 8, v116
	v_lshl_add_u64 v[48:49], s[10:11], 1, v[48:49]
	v_lshlrev_b32_e32 v160, 1, v50
	v_min_i32_e32 v86, 0xffffffef, v170
	v_lshl_add_u64 v[48:49], v[48:49], 0, v[160:161]
	s_mov_b64 s[10:11], 0x4000
	v_min_i32_e32 v66, 11, v170
	v_ashrrev_i32_e32 v87, 31, v86
	v_lshl_add_u64 v[64:65], v[48:49], 0, s[10:11]
	v_min_i32_e32 v48, 15, v170
	v_or_b32_e32 v66, 4, v66
	v_lshlrev_b64 v[86:87], 12, v[86:87]
	v_min_i32_e32 v102, 0xffffffeb, v170
	v_ashrrev_i32_e32 v49, 31, v48
	v_ashrrev_i32_e32 v67, 31, v66
	v_lshl_add_u64 v[86:87], v[70:71], 0, v[86:87]
	s_mov_b64 s[10:11], 0x20000
	s_mov_b32 s5, 0x20000
	v_ashrrev_i32_e32 v103, 31, v102
	v_lshlrev_b64 v[48:49], 12, v[48:49]
	v_lshlrev_b64 v[66:67], 12, v[66:67]
	v_lshl_add_u64 v[98:99], v[86:87], 0, s[10:11]
	v_add_co_u32_e32 v86, vcc, s5, v86
	v_lshlrev_b64 v[102:103], 12, v[102:103]
	v_lshl_add_u64 v[60:61], v[70:71], 0, v[48:49]
	v_lshl_add_u64 v[82:83], v[70:71], 0, v[66:67]
	v_addc_co_u32_e32 v87, vcc, 0, v87, vcc
	v_lshl_add_u64 v[70:71], v[70:71], 0, v[102:103]
	s_mov_b64 s[10:11], 0x24000
	s_mov_b32 s5, 0x24000
	v_lshl_add_u64 v[114:115], v[70:71], 0, s[10:11]
	v_add_co_u32_e32 v70, vcc, s5, v70
	flat_load_dwordx4 v[48:51], v[60:61]
	flat_load_dwordx4 v[52:55], v[60:61] offset:64
	flat_load_dwordx4 v[56:59], v[60:61] offset:128
	s_nop 0
	flat_load_dwordx4 v[60:63], v[60:61] offset:192
	v_addc_co_u32_e32 v71, vcc, 0, v71, vcc
	flat_load_dwordx4 v[66:69], v[82:83]
	flat_load_dwordx4 v[74:77], v[82:83] offset:64
	flat_load_dwordx4 v[78:81], v[82:83] offset:128
	s_nop 0
	flat_load_dwordx4 v[82:85], v[82:83] offset:192
	s_nop 0
	flat_load_dwordx4 v[86:89], v[86:87]
	s_nop 0
	flat_load_dwordx4 v[90:93], v[98:99] offset:64
	flat_load_dwordx4 v[94:97], v[98:99] offset:128
	s_nop 0
	flat_load_dwordx4 v[98:101], v[98:99] offset:192
	s_nop 0
	flat_load_dwordx4 v[102:105], v[70:71]
	flat_load_dwordx4 v[106:109], v[114:115] offset:64
	flat_load_dwordx4 v[110:113], v[114:115] offset:128
	s_nop 0
	flat_load_dwordx4 v[114:117], v[114:115] offset:192
	s_waitcnt vmcnt(0) lgkmcnt(0)
	v_mfma_f32_16x16x32_bf16 v[48:51], v[48:51], v[32:35], 0
	v_mfma_f32_16x16x32_bf16 v[48:51], v[52:55], v[36:39], v[48:51]
	v_mfma_f32_16x16x32_bf16 v[48:51], v[56:59], v[40:43], v[48:51]
	v_mfma_f32_16x16x32_bf16 v[60:63], v[60:63], v[44:47], v[48:51]
	v_mfma_f32_16x16x32_bf16 v[48:51], v[66:69], v[32:35], 0
	v_mfma_f32_16x16x32_bf16 v[48:51], v[74:77], v[36:39], v[48:51]
	v_mfma_f32_16x16x32_bf16 v[48:51], v[78:81], v[40:43], v[48:51]
	v_mfma_f32_16x16x32_bf16 v[56:59], v[82:85], v[44:47], v[48:51]
	v_mfma_f32_16x16x32_bf16 v[48:51], v[86:89], v[32:35], 0
	v_mfma_f32_16x16x32_bf16 v[32:35], v[102:105], v[32:35], 0
	v_mfma_f32_16x16x32_bf16 v[48:51], v[90:93], v[36:39], v[48:51]
	v_mfma_f32_16x16x32_bf16 v[32:35], v[106:109], v[36:39], v[32:35]
	v_mfma_f32_16x16x32_bf16 v[48:51], v[94:97], v[40:43], v[48:51]
	v_mfma_f32_16x16x32_bf16 v[32:35], v[110:113], v[40:43], v[32:35]
	v_mfma_f32_16x16x32_bf16 v[52:55], v[98:101], v[44:47], v[48:51]
	v_mfma_f32_16x16x32_bf16 v[48:51], v[114:117], v[44:47], v[32:35]
	v_cmp_gt_i32_e64 s[10:11], 2, v167
	s_nop 4
	v_mov_b32_e32 v32, 0
	v_mov_b32_e32 v36, 0
	v_mov_b32_e32 v37, 0
	v_mov_b32_e32 v38, 0
	v_mov_b32_e32 v39, 0
	s_and_saveexec_b64 s[14:15], s[10:11]
	s_cbranch_execz .LBB0_509
	flat_load_dwordx4 v[36:39], v[64:65]
